# prompt attention: K by LDS-DMA + V loads at half-step start (5 of 6 half-steps) combined with partialSM between the P.V MFMAs
# baseline (speedup 1.0000x reference)
.LBB0_1167:
	v_readfirstlane_b32 s8, v176
	v_lshrrev_b32_e32 v234, 4, v176
	v_lshl_add_u64 v[230:231], v[158:159], 0, v[96:97]
	s_and_b32 s8, s8, 0xfffffc00
	v_and_b32_e32 v234, 0x70, v234
	s_add_i32 m0, s8, 0x8000
	v_xor_b32_e32 v230, v234, v230
	v_lshl_add_u64 v[242:243], v[156:157], 0, v[96:97]
	global_load_lds_dwordx4 v[230:231], off
	v_lshl_add_u64 v[230:231], v[154:155], 0, v[96:97]
	s_add_i32 m0, s8, 0xa000
	v_xor_b32_e32 v230, v234, v230
	v_lshl_add_u64 v[246:247], v[152:153], 0, v[96:97]
	global_load_lds_dwordx4 v[230:231], off
	global_load_dwordx4 v[242:245], v[242:243], off
	global_load_dwordx4 v[246:249], v[246:247], off
	ds_read_b128 v[80:83], v189
	ds_read_b128 v[84:87], v189 offset:32
	ds_read_b128 v[64:67], v189 offset:128
	ds_read_b128 v[68:71], v189 offset:160
	ds_read_b128 v[88:91], v189 offset:64
	ds_read_b128 v[72:75], v189 offset:192
	ds_read_b128 v[92:95], v189 offset:96
	ds_read_b128 v[76:79], v189 offset:224
	ds_read_b128 v[206:209], v181 offset:49152
	ds_read_b128 v[210:213], v181 offset:57344
	v_add_f32_e32 v146, 0, v147
	v_add_f32_e32 v146, v148, v146
	v_add_f32_e32 v146, v149, v146
	s_waitcnt lgkmcnt(1)
	v_mfma_f32_32x32x16_bf16 v[80:95], v[206:209], v[126:129], v[80:95]
	v_add_f32_e32 v146, v202, v146
	v_add_f32_e32 v146, v203, v146
	v_add_f32_e32 v146, v205, v146
	v_add_f32_e32 v146, v201, v146
	v_add_f32_e32 v146, v204, v146
	v_add_f32_e32 v146, v193, v146
	v_add_f32_e32 v146, v195, v146
	s_waitcnt lgkmcnt(0)
	v_mfma_f32_32x32x16_bf16 v[64:79], v[210:213], v[126:129], v[64:79]
	ds_read_b128 v[206:209], v182 offset:49152
	ds_read_b128 v[210:213], v182 offset:57344
	v_add_f32_e32 v146, v196, v146
	v_add_f32_e32 v146, v199, v146
	v_exp_f32_e32 v142, v142
	v_add_f32_e32 v146, v194, v146
	v_exp_f32_e32 v143, v143
	v_add_f32_e32 v146, v197, v146
	s_waitcnt lgkmcnt(1)
	v_mfma_f32_32x32x16_bf16 v[80:95], v[206:209], v[122:125], v[80:95]
	v_exp_f32_e32 v140, v140
	v_add_f32_e32 v146, v198, v146
	v_exp_f32_e32 v141, v141
	v_add_f32_e32 v146, v200, v146
	v_exp_f32_e32 v136, v136
	v_add_f32_e32 v146, v142, v146
	v_exp_f32_e32 v137, v137
	s_waitcnt lgkmcnt(0)
	v_mfma_f32_32x32x16_bf16 v[64:79], v[210:213], v[122:125], v[64:79]
	ds_read_b128 v[206:209], v180 offset:49152
	ds_read_b128 v[210:213], v180 offset:57344
	v_add_f32_e32 v146, v143, v146
	v_exp_f32_e32 v134, v134
	v_add_f32_e32 v146, v140, v146
	v_exp_f32_e32 v135, v135
	v_add_f32_e32 v146, v141, v146
	v_exp_f32_e32 v130, v130
	s_waitcnt lgkmcnt(1)
	v_mfma_f32_32x32x16_bf16 v[80:95], v[206:209], v[118:121], v[80:95]
	v_add_f32_e32 v146, v136, v146
	v_exp_f32_e32 v131, v131
	v_add_f32_e32 v146, v137, v146
	v_exp_f32_e32 v144, v144
	v_add_f32_e32 v146, v134, v146
	v_exp_f32_e32 v145, v145
	v_add_f32_e32 v146, v135, v146
	s_waitcnt lgkmcnt(0)
	v_mfma_f32_32x32x16_bf16 v[64:79], v[210:213], v[118:121], v[64:79]
	ds_read_b128 v[206:209], v151 offset:49152
	ds_read_b128 v[210:213], v151 offset:57344
	v_exp_f32_e32 v138, v138
	v_add_f32_e32 v146, v130, v146
	v_exp_f32_e32 v139, v139
	v_add_f32_e32 v146, v131, v146
	v_exp_f32_e32 v132, v132
	v_add_f32_e32 v146, v144, v146
	s_waitcnt lgkmcnt(1)
	v_mfma_f32_32x32x16_bf16 v[80:95], v[206:209], v[114:117], v[80:95]
	v_exp_f32_e32 v133, v133
	v_add_f32_e32 v146, v145, v146
	v_add_f32_e32 v146, v138, v146
	v_add_f32_e32 v146, v139, v146
	v_add_f32_e32 v146, v132, v146
	v_add_f32_e32 v190, v133, v146
	v_mov_b32_e32 v191, v190
	s_waitcnt lgkmcnt(0)
	v_mfma_f32_32x32x16_bf16 v[64:79], v[210:213], v[114:117], v[64:79]
	ds_read_b128 v[206:209], v181 offset:49280
	ds_read_b128 v[210:213], v181 offset:57472
	v_permlane32_swap_b32_e32 v190, v191
	v_cvt_pk_bf16_f32 v146, v147, v148
	v_cvt_pk_bf16_f32 v147, v149, v202
	v_cvt_pk_bf16_f32 v148, v203, v205
	v_cvt_pk_bf16_f32 v149, v201, v204
	s_waitcnt lgkmcnt(1)
	v_mfma_f32_32x32x16_bf16 v[80:95], v[206:209], v[110:113], v[80:95]
	v_cvt_pk_bf16_f32 v192, v193, v195
	v_cvt_pk_bf16_f32 v193, v196, v199
	v_cvt_pk_bf16_f32 v194, v194, v197
	v_cvt_pk_bf16_f32 v195, v198, v200
	v_cvt_pk_bf16_f32 v196, v142, v143
	v_cvt_pk_bf16_f32 v197, v140, v141
	v_cvt_pk_bf16_f32 v198, v136, v137
	s_waitcnt lgkmcnt(0)
	v_mfma_f32_32x32x16_bf16 v[64:79], v[210:213], v[110:113], v[64:79]
	ds_read_b128 v[206:209], v182 offset:49280
	ds_read_b128 v[210:213], v182 offset:57472
	v_cvt_pk_bf16_f32 v199, v134, v135
	v_cvt_pk_bf16_f32 v200, v130, v131
	v_cvt_pk_bf16_f32 v201, v144, v145
	v_cvt_pk_bf16_f32 v202, v138, v139
	v_cvt_pk_bf16_f32 v203, v132, v133
	v_permlane32_swap_b32_e32 v146, v148
	s_waitcnt lgkmcnt(1)
	v_mfma_f32_32x32x16_bf16 v[80:95], v[206:209], v[106:109], v[80:95]
	v_permlane32_swap_b32_e32 v147, v149
	v_permlane32_swap_b32_e32 v192, v194
	v_permlane32_swap_b32_e32 v193, v195
	v_permlane32_swap_b32_e32 v196, v198
	s_waitcnt lgkmcnt(0)
	v_mfma_f32_32x32x16_bf16 v[64:79], v[210:213], v[106:109], v[64:79]
	ds_read_b128 v[206:209], v180 offset:49280
	ds_read_b128 v[210:213], v180 offset:57472
	v_permlane32_swap_b32_e32 v197, v199
	v_permlane32_swap_b32_e32 v200, v202
	v_permlane32_swap_b32_e32 v201, v203
	s_waitcnt lgkmcnt(1)
	v_mfma_f32_32x32x16_bf16 v[80:95], v[206:209], v[102:105], v[80:95]
	s_waitcnt lgkmcnt(0)
	v_mfma_f32_32x32x16_bf16 v[64:79], v[210:213], v[102:105], v[64:79]
	ds_read_b128 v[206:209], v151 offset:49280
	ds_read_b128 v[210:213], v151 offset:57472
	s_waitcnt lgkmcnt(1)
	v_mfma_f32_32x32x16_bf16 v[80:95], v[206:209], v[98:101], v[80:95]
	s_waitcnt lgkmcnt(0)
	v_mfma_f32_32x32x16_bf16 v[64:79], v[210:213], v[98:101], v[64:79]
	s_sub_i32 s6, s92, 64
	s_cmp_le_i32 s6, s41
	s_cbranch_scc0 .Lpvm_1167a
	ds_read_b64_tr_b16 v[204:205], v174 offset:0
	ds_read_b64_tr_b16 v[206:207], v174 offset:0x800
	ds_read_b64_tr_b16 v[208:209], v174 offset:0x1000
	ds_read_b64_tr_b16 v[210:211], v174 offset:0x1800
	ds_read_b64_tr_b16 v[220:221], v174 offset:0x2000
	ds_read_b64_tr_b16 v[222:223], v174 offset:0x2800
	ds_read_b64_tr_b16 v[224:225], v174 offset:0x3000
	ds_read_b64_tr_b16 v[226:227], v174 offset:0x3800
	s_waitcnt lgkmcnt(0)
	s_nop 0
	v_mfma_f32_32x32x16_bf16 v[48:63], v[146:149], v[204:207], v[48:63]
	v_max_f32_e32 v230, v81, v81
	v_max_f32_e32 v231, v80, v80
	v_max_f32_e32 v230, v231, v230
	ds_read_b64_tr_b16 v[204:205], v174 offset:0x200
	ds_read_b64_tr_b16 v[206:207], v174 offset:0xa00
	v_mfma_f32_32x32x16_bf16 v[48:63], v[192:195], v[208:211], v[48:63]
	v_max3_f32 v230, v230, v82, v83
	v_max3_f32 v230, v230, v84, v85
	v_max3_f32 v230, v230, v86, v87
	ds_read_b64_tr_b16 v[208:209], v174 offset:0x1200
	ds_read_b64_tr_b16 v[210:211], v174 offset:0x1a00
	v_mfma_f32_32x32x16_bf16 v[48:63], v[196:199], v[220:223], v[48:63]
	v_max3_f32 v230, v230, v88, v89
	v_max3_f32 v230, v230, v90, v91
	v_max3_f32 v230, v230, v92, v93
	ds_read_b64_tr_b16 v[220:221], v174 offset:0x2200
	ds_read_b64_tr_b16 v[222:223], v174 offset:0x2a00
	v_mfma_f32_32x32x16_bf16 v[48:63], v[200:203], v[224:227], v[48:63]
	v_max3_f32 v230, v230, v94, v95
	v_max3_f32 v230, v230, v64, v65
	v_max3_f32 v230, v230, v66, v67
	ds_read_b64_tr_b16 v[224:225], v174 offset:0x3200
	ds_read_b64_tr_b16 v[226:227], v174 offset:0x3a00
	s_waitcnt lgkmcnt(0)
	v_mfma_f32_32x32x16_bf16 v[32:47], v[146:149], v[204:207], v[32:47]
	v_max3_f32 v230, v230, v68, v69
	v_max3_f32 v230, v230, v70, v71
	v_max3_f32 v230, v230, v72, v73
	ds_read_b64_tr_b16 v[204:205], v174 offset:0x400
	ds_read_b64_tr_b16 v[206:207], v174 offset:0xc00
	v_mfma_f32_32x32x16_bf16 v[32:47], v[192:195], v[208:211], v[32:47]
	v_max3_f32 v230, v230, v74, v75
	v_max3_f32 v230, v230, v76, v77
	v_max3_f32 v230, v230, v78, v79
	ds_read_b64_tr_b16 v[208:209], v174 offset:0x1400
	ds_read_b64_tr_b16 v[210:211], v174 offset:0x1c00
	v_mfma_f32_32x32x16_bf16 v[32:47], v[196:199], v[220:223], v[32:47]
	v_mov_b32_e32 v231, v230
	s_nop 1
	v_permlane32_swap_b32_e32 v230, v231
	ds_read_b64_tr_b16 v[220:221], v174 offset:0x2400
	ds_read_b64_tr_b16 v[222:223], v174 offset:0x2c00
	v_mfma_f32_32x32x16_bf16 v[32:47], v[200:203], v[224:227], v[32:47]
	v_max_f32_e32 v231, v231, v231
	v_max_f32_e32 v230, v230, v230
	v_max_f32_e32 v230, v230, v231
	ds_read_b64_tr_b16 v[224:225], v174 offset:0x3400
	ds_read_b64_tr_b16 v[226:227], v174 offset:0x3c00
	s_waitcnt lgkmcnt(0)
	v_mfma_f32_32x32x16_bf16 v[16:31], v[146:149], v[204:207], v[16:31]
	v_sub_f32_e32 v231, v230, v187
	v_mul_f32_e32 v231, 0x3db504f3, v231
	s_mov_b32 s6, 0x41000000
	ds_read_b64_tr_b16 v[204:205], v174 offset:0x600
	ds_read_b64_tr_b16 v[206:207], v174 offset:0xe00
	v_mfma_f32_32x32x16_bf16 v[16:31], v[192:195], v[208:211], v[16:31]
	v_cmp_ge_f32_e32 vcc, s6, v231
	v_max_f32_e32 v231, v187, v187
	v_max_f32_e32 v230, v231, v230
	ds_read_b64_tr_b16 v[208:209], v174 offset:0x1600
	ds_read_b64_tr_b16 v[210:211], v174 offset:0x1e00
	v_mfma_f32_32x32x16_bf16 v[16:31], v[196:199], v[220:223], v[16:31]
	v_sub_f32_e32 v231, v187, v230
	v_mul_f32_e32 v231, 0x3e0293ee, v231
	v_exp_f32_e32 v231, v231
	ds_read_b64_tr_b16 v[220:221], v174 offset:0x2600
	ds_read_b64_tr_b16 v[222:223], v174 offset:0x2e00
	v_mfma_f32_32x32x16_bf16 v[16:31], v[200:203], v[224:227], v[16:31]
	ds_read_b64_tr_b16 v[224:225], v174 offset:0x3600
	ds_read_b64_tr_b16 v[226:227], v174 offset:0x3e00
	s_waitcnt lgkmcnt(0)
	v_mfma_f32_32x32x16_bf16 v[0:15], v[146:149], v[204:207], v[0:15]
	v_mfma_f32_32x32x16_bf16 v[0:15], v[192:195], v[208:211], v[0:15]
	v_mfma_f32_32x32x16_bf16 v[0:15], v[196:199], v[220:223], v[0:15]
	v_mfma_f32_32x32x16_bf16 v[0:15], v[200:203], v[224:227], v[0:15]
	s_nop 0
	v_mov_b32_e32 v146, v230
	v_mov_b32_e32 v147, v231
	s_branch .Lpvj_1167a

.Lpvj_1167a:
	s_cmp_eq_u64 vcc, exec
	s_cselect_b64 s[6:7], -1, 0
	s_barrier
	s_waitcnt vmcnt(0)
	v_cndmask_b32_e64 v192, v147, 1.0, s[6:7]
	v_cmp_gt_f32_e32 vcc, 1.0, v192
	s_waitcnt vmcnt(0)
	ds_write_b128 v184, v[242:245]
	ds_write_b128 v185, v[246:249]
	s_cbranch_vccz .LBB0_1173
	s_and_saveexec_b64 s[8:9], s[4:5]
	ds_write_b32 v173, v192 offset:128
	s_or_b64 exec, exec, s[8:9]
	s_waitcnt lgkmcnt(0)
	ds_read_b128 v[130:133], v169 offset:224
	ds_read_b128 v[134:137], v169 offset:192
	ds_read_b128 v[138:141], v169 offset:160
	ds_read_b128 v[142:145], v169 offset:128
	s_waitcnt lgkmcnt(3)
	v_pk_mul_f32 v[62:63], v[62:63], v[132:133]
	s_waitcnt lgkmcnt(2)
	v_pk_mul_f32 v[58:59], v[58:59], v[136:137]
	s_waitcnt lgkmcnt(1)
	v_pk_mul_f32 v[54:55], v[54:55], v[140:141]
	s_waitcnt lgkmcnt(0)
	v_pk_mul_f32 v[50:51], v[50:51], v[144:145]
	v_pk_mul_f32 v[60:61], v[60:61], v[130:131]
	v_pk_mul_f32 v[56:57], v[56:57], v[134:135]
	v_pk_mul_f32 v[52:53], v[52:53], v[138:139]
	v_pk_mul_f32 v[48:49], v[48:49], v[142:143]
	v_pk_mul_f32 v[46:47], v[46:47], v[132:133]
	v_pk_mul_f32 v[42:43], v[42:43], v[136:137]
	v_pk_mul_f32 v[38:39], v[38:39], v[140:141]
	v_pk_mul_f32 v[34:35], v[34:35], v[144:145]
	v_pk_mul_f32 v[44:45], v[44:45], v[130:131]
	v_pk_mul_f32 v[40:41], v[40:41], v[134:135]
	v_pk_mul_f32 v[36:37], v[36:37], v[138:139]
	v_pk_mul_f32 v[32:33], v[32:33], v[142:143]
	v_pk_mul_f32 v[30:31], v[30:31], v[132:133]
	v_pk_mul_f32 v[26:27], v[26:27], v[136:137]
	v_pk_mul_f32 v[22:23], v[22:23], v[140:141]
	v_pk_mul_f32 v[18:19], v[18:19], v[144:145]
	v_pk_mul_f32 v[28:29], v[28:29], v[130:131]
	v_pk_mul_f32 v[24:25], v[24:25], v[134:135]
	v_pk_mul_f32 v[20:21], v[20:21], v[138:139]
	v_pk_mul_f32 v[16:17], v[16:17], v[142:143]
	v_pk_mul_f32 v[14:15], v[14:15], v[132:133]
	v_pk_mul_f32 v[10:11], v[10:11], v[136:137]
	v_pk_mul_f32 v[6:7], v[6:7], v[140:141]
	v_pk_mul_f32 v[2:3], v[2:3], v[144:145]
	v_pk_mul_f32 v[12:13], v[12:13], v[130:131]
	v_pk_mul_f32 v[8:9], v[8:9], v[134:135]
	v_pk_mul_f32 v[4:5], v[4:5], v[138:139]
	v_pk_mul_f32 v[0:1], v[0:1], v[142:143]
.LBB0_1173:
	v_cndmask_b32_e64 v187, v146, v187, s[6:7]
	v_mul_f32_e32 v146, 0xbe0293ee, v187
	v_fmamk_f32 v80, v80, 0x3e0293ee, v146
	v_fmamk_f32 v81, v81, 0x3e0293ee, v146
	v_fmamk_f32 v82, v82, 0x3e0293ee, v146
	v_fmamk_f32 v83, v83, 0x3e0293ee, v146
	v_fmamk_f32 v84, v84, 0x3e0293ee, v146
	v_fmamk_f32 v85, v85, 0x3e0293ee, v146
	v_fmamk_f32 v86, v86, 0x3e0293ee, v146
	v_fmamk_f32 v87, v87, 0x3e0293ee, v146
	v_fmamk_f32 v88, v88, 0x3e0293ee, v146
	v_fmamk_f32 v89, v89, 0x3e0293ee, v146
	v_fmamk_f32 v90, v90, 0x3e0293ee, v146
	v_fmamk_f32 v91, v91, 0x3e0293ee, v146
	v_fmamk_f32 v92, v92, 0x3e0293ee, v146
	v_fmamk_f32 v93, v93, 0x3e0293ee, v146
	v_fmamk_f32 v94, v94, 0x3e0293ee, v146
	v_fmamk_f32 v95, v95, 0x3e0293ee, v146
	v_exp_f32_e32 v139, v80
	v_exp_f32_e32 v141, v81
	v_exp_f32_e32 v142, v82
	v_exp_f32_e32 v143, v83
	v_exp_f32_e32 v144, v84
	v_exp_f32_e32 v145, v85
	v_exp_f32_e32 v138, v86
	v_exp_f32_e32 v140, v87
	v_exp_f32_e32 v133, v88
	v_exp_f32_e32 v135, v89
	v_exp_f32_e32 v136, v90
	v_exp_f32_e32 v137, v91
	v_exp_f32_e32 v130, v92
	v_exp_f32_e32 v131, v93
	v_exp_f32_e32 v132, v94
	v_exp_f32_e32 v134, v95
	v_fmamk_f32 v198, v64, 0x3e0293ee, v146
	v_fmamk_f32 v199, v65, 0x3e0293ee, v146
	v_fmamk_f32 v200, v66, 0x3e0293ee, v146
	v_fmamk_f32 v201, v67, 0x3e0293ee, v146
	v_fmamk_f32 v202, v68, 0x3e0293ee, v146
	v_fmamk_f32 v148, v69, 0x3e0293ee, v146
	v_fmamk_f32 v149, v70, 0x3e0293ee, v146
	v_fmamk_f32 v193, v71, 0x3e0293ee, v146
	v_fmamk_f32 v194, v72, 0x3e0293ee, v146
	v_fmamk_f32 v195, v73, 0x3e0293ee, v146
	v_fmamk_f32 v196, v74, 0x3e0293ee, v146
	v_fmamk_f32 v197, v75, 0x3e0293ee, v146
	v_fmamk_f32 v147, v76, 0x3e0293ee, v146
	v_fmamk_f32 v203, v77, 0x3e0293ee, v146
	v_fmamk_f32 v204, v78, 0x3e0293ee, v146
	v_fmac_f32_e32 v146, 0x3e0293ee, v79
	s_waitcnt lgkmcnt(0)
	s_barrier
	v_readfirstlane_b32 s8, v176
	v_lshrrev_b32_e32 v234, 4, v176
	v_lshl_add_u64 v[230:231], v[166:167], 0, v[96:97]
	s_and_b32 s8, s8, 0xfffffc00
	v_and_b32_e32 v234, 0x70, v234
	s_add_i32 m0, s8, 0xc000
	v_xor_b32_e32 v230, v234, v230
	v_lshl_add_u64 v[242:243], v[164:165], 0, v[96:97]
	global_load_lds_dwordx4 v[230:231], off
	v_lshl_add_u64 v[230:231], v[162:163], 0, v[96:97]
	s_add_i32 m0, s8, 0xe000
	v_xor_b32_e32 v230, v234, v230
	v_lshl_add_u64 v[246:247], v[160:161], 0, v[96:97]
	global_load_lds_dwordx4 v[230:231], off
	global_load_dwordx4 v[242:245], v[242:243], off
	global_load_dwordx4 v[246:249], v[246:247], off
	ds_read_b128 v[80:83], v189 offset:256
	ds_read_b128 v[84:87], v189 offset:288
	ds_read_b128 v[64:67], v189 offset:384
	ds_read_b128 v[68:71], v189 offset:416
	ds_read_b128 v[88:91], v189 offset:320
	ds_read_b128 v[72:75], v189 offset:448
	ds_read_b128 v[92:95], v189 offset:352
	ds_read_b128 v[76:79], v189 offset:480
	ds_read_b128 v[206:209], v181 offset:32768
	ds_read_b128 v[210:213], v181 offset:40960
	v_exp_f32_e32 v218, v146
	v_add_f32_e32 v146, 0, v139
	v_add_f32_e32 v146, v141, v146
	s_waitcnt lgkmcnt(1)
	v_mfma_f32_32x32x16_bf16 v[80:95], v[206:209], v[126:129], v[80:95]
	v_add_f32_e32 v146, v142, v146
	v_add_f32_e32 v146, v143, v146
	v_add_f32_e32 v146, v144, v146
	v_add_f32_e32 v146, v145, v146
	v_add_f32_e32 v146, v138, v146
	v_add_f32_e32 v146, v140, v146
	v_add_f32_e32 v146, v133, v146
	s_waitcnt lgkmcnt(0)
	v_mfma_f32_32x32x16_bf16 v[64:79], v[210:213], v[126:129], v[64:79]
	ds_read_b128 v[206:209], v182 offset:32768
	ds_read_b128 v[210:213], v182 offset:40960
	v_add_f32_e32 v146, v135, v146
	v_add_f32_e32 v146, v136, v146
	v_add_f32_e32 v146, v137, v146
	v_exp_f32_e32 v198, v198
	v_add_f32_e32 v146, v130, v146
	v_exp_f32_e32 v199, v199
	s_waitcnt lgkmcnt(1)
	v_mfma_f32_32x32x16_bf16 v[80:95], v[206:209], v[122:125], v[80:95]
	v_add_f32_e32 v146, v131, v146
	v_exp_f32_e32 v200, v200
	v_add_f32_e32 v146, v132, v146
	v_exp_f32_e32 v201, v201
	v_add_f32_e32 v146, v134, v146
	v_exp_f32_e32 v202, v202
	v_add_f32_e32 v146, v198, v146
	s_waitcnt lgkmcnt(0)
	v_mfma_f32_32x32x16_bf16 v[64:79], v[210:213], v[122:125], v[64:79]
	ds_read_b128 v[206:209], v180 offset:32768
	ds_read_b128 v[210:213], v180 offset:40960
	v_exp_f32_e32 v205, v148
	v_add_f32_e32 v146, v199, v146
	v_add_f32_e32 v146, v200, v146
	v_exp_f32_e32 v193, v193
	v_add_f32_e32 v146, v201, v146
	v_add_f32_e32 v146, v202, v146
	s_waitcnt lgkmcnt(1)
	v_mfma_f32_32x32x16_bf16 v[80:95], v[206:209], v[118:121], v[80:95]
	v_add_f32_e32 v146, v205, v146
	v_exp_f32_e32 v214, v203
	v_exp_f32_e32 v215, v204
	v_cvt_pk_bf16_f32 v148, v144, v145
	v_cvt_pk_bf16_f32 v198, v198, v199
	v_cvt_pk_bf16_f32 v199, v200, v201
	v_cvt_pk_bf16_f32 v200, v202, v205
	s_waitcnt lgkmcnt(0)
	v_mfma_f32_32x32x16_bf16 v[64:79], v[210:213], v[118:121], v[64:79]
	ds_read_b128 v[206:209], v151 offset:32768
	ds_read_b128 v[210:213], v151 offset:40960
	v_cvt_pk_bf16_f32 v205, v215, v218
	v_permlane32_swap_b32_e32 v198, v200
	s_waitcnt lgkmcnt(1)
	v_mfma_f32_32x32x16_bf16 v[80:95], v[206:209], v[114:117], v[80:95]
	s_waitcnt lgkmcnt(0)
	v_mfma_f32_32x32x16_bf16 v[64:79], v[210:213], v[114:117], v[64:79]
	ds_read_b128 v[206:209], v181 offset:32896
	ds_read_b128 v[210:213], v181 offset:41088
	s_waitcnt lgkmcnt(1)
	v_mfma_f32_32x32x16_bf16 v[80:95], v[206:209], v[110:113], v[80:95]
	s_waitcnt lgkmcnt(0)
	v_mfma_f32_32x32x16_bf16 v[64:79], v[210:213], v[110:113], v[64:79]
	ds_read_b128 v[206:209], v182 offset:32896
	ds_read_b128 v[210:213], v182 offset:41088
	s_waitcnt lgkmcnt(1)
	v_mfma_f32_32x32x16_bf16 v[80:95], v[206:209], v[106:109], v[80:95]
	s_waitcnt lgkmcnt(0)
	v_mfma_f32_32x32x16_bf16 v[64:79], v[210:213], v[106:109], v[64:79]
	ds_read_b128 v[206:209], v180 offset:32896
	ds_read_b128 v[210:213], v180 offset:41088
	s_waitcnt lgkmcnt(1)
	v_mfma_f32_32x32x16_bf16 v[80:95], v[206:209], v[102:105], v[80:95]
	s_waitcnt lgkmcnt(0)
	v_mfma_f32_32x32x16_bf16 v[64:79], v[210:213], v[102:105], v[64:79]
	ds_read_b128 v[206:209], v151 offset:32896
	ds_read_b128 v[210:213], v151 offset:41088
	s_waitcnt lgkmcnt(1)
	v_mfma_f32_32x32x16_bf16 v[80:95], v[206:209], v[98:101], v[80:95]
	v_exp_f32_e32 v208, v149
	v_exp_f32_e32 v209, v194
	v_cvt_pk_bf16_f32 v149, v138, v140
	v_cvt_pk_bf16_f32 v194, v133, v135
	v_add_f32_e32 v146, v208, v146
	v_add_f32_e32 v146, v193, v146
	v_add_f32_e32 v146, v209, v146
	s_waitcnt lgkmcnt(0)
	v_mfma_f32_32x32x16_bf16 v[64:79], v[210:213], v[98:101], v[64:79]
	v_exp_f32_e32 v210, v195
	v_exp_f32_e32 v211, v196
	v_exp_f32_e32 v212, v197
	v_exp_f32_e32 v213, v147
	v_add_f32_e32 v146, v210, v146
	v_add_f32_e32 v146, v211, v146
	v_add_f32_e32 v146, v212, v146
	v_add_f32_e32 v146, v213, v146
	v_add_f32_e32 v146, v214, v146
	v_add_f32_e32 v146, v215, v146
	v_add_f32_e32 v206, v218, v146
	v_mov_b32_e32 v207, v206
	s_nop 1
	v_permlane32_swap_b32_e32 v206, v207
	v_cvt_pk_bf16_f32 v146, v139, v141
	v_cvt_pk_bf16_f32 v147, v142, v143
	v_cvt_pk_bf16_f32 v195, v136, v137
	v_cvt_pk_bf16_f32 v196, v130, v131
	v_cvt_pk_bf16_f32 v197, v132, v134
	v_cvt_pk_bf16_f32 v201, v208, v193
	v_cvt_pk_bf16_f32 v202, v209, v210
	v_cvt_pk_bf16_f32 v203, v211, v212
	v_cvt_pk_bf16_f32 v204, v213, v214
	v_permlane32_swap_b32_e32 v146, v148
	v_permlane32_swap_b32_e32 v147, v149
	v_permlane32_swap_b32_e32 v194, v196
	v_permlane32_swap_b32_e32 v195, v197
	v_permlane32_swap_b32_e32 v199, v201
	v_permlane32_swap_b32_e32 v202, v204
	v_permlane32_swap_b32_e32 v203, v205
	s_cmp_le_i32 s92, s41
	s_cbranch_scc0 .Lpvm_1167b
	ds_read_b64_tr_b16 v[208:209], v174 offset:0x4000
	ds_read_b64_tr_b16 v[210:211], v174 offset:0x4800
	ds_read_b64_tr_b16 v[220:221], v174 offset:0x5000
	ds_read_b64_tr_b16 v[222:223], v174 offset:0x5800
	ds_read_b64_tr_b16 v[224:225], v174 offset:0x6000
	ds_read_b64_tr_b16 v[226:227], v174 offset:0x6800
	ds_read_b64_tr_b16 v[238:239], v174 offset:0x7000
	ds_read_b64_tr_b16 v[240:241], v174 offset:0x7800
	s_waitcnt lgkmcnt(0)
	s_nop 0
	v_mfma_f32_32x32x16_bf16 v[48:63], v[146:149], v[208:211], v[48:63]
	v_max_f32_e32 v230, v81, v81
	v_max_f32_e32 v231, v80, v80
	v_max_f32_e32 v230, v231, v230
	ds_read_b64_tr_b16 v[208:209], v174 offset:0x4200
	ds_read_b64_tr_b16 v[210:211], v174 offset:0x4a00
	v_mfma_f32_32x32x16_bf16 v[48:63], v[194:197], v[220:223], v[48:63]
	v_max3_f32 v230, v230, v82, v83
	v_max3_f32 v230, v230, v84, v85
	v_max3_f32 v230, v230, v86, v87
	ds_read_b64_tr_b16 v[220:221], v174 offset:0x5200
	ds_read_b64_tr_b16 v[222:223], v174 offset:0x5a00
	v_mfma_f32_32x32x16_bf16 v[48:63], v[198:201], v[224:227], v[48:63]
	v_max3_f32 v230, v230, v88, v89
	v_max3_f32 v230, v230, v90, v91
	v_max3_f32 v230, v230, v92, v93
	ds_read_b64_tr_b16 v[224:225], v174 offset:0x6200
	ds_read_b64_tr_b16 v[226:227], v174 offset:0x6a00
	v_mfma_f32_32x32x16_bf16 v[48:63], v[202:205], v[238:241], v[48:63]
	v_max3_f32 v230, v230, v94, v95
	v_max3_f32 v230, v230, v64, v65
	v_max3_f32 v230, v230, v66, v67
	ds_read_b64_tr_b16 v[238:239], v174 offset:0x7200
	ds_read_b64_tr_b16 v[240:241], v174 offset:0x7a00
	s_waitcnt lgkmcnt(0)
	v_mfma_f32_32x32x16_bf16 v[32:47], v[146:149], v[208:211], v[32:47]
	v_max3_f32 v230, v230, v68, v69
	v_max3_f32 v230, v230, v70, v71
	v_max3_f32 v230, v230, v72, v73
	ds_read_b64_tr_b16 v[208:209], v174 offset:0x4400
	ds_read_b64_tr_b16 v[210:211], v174 offset:0x4c00
	v_mfma_f32_32x32x16_bf16 v[32:47], v[194:197], v[220:223], v[32:47]
	v_max3_f32 v230, v230, v74, v75
	v_max3_f32 v230, v230, v76, v77
	v_max3_f32 v230, v230, v78, v79
	ds_read_b64_tr_b16 v[220:221], v174 offset:0x5400
	ds_read_b64_tr_b16 v[222:223], v174 offset:0x5c00
	v_mfma_f32_32x32x16_bf16 v[32:47], v[198:201], v[224:227], v[32:47]
	v_mov_b32_e32 v231, v230
	s_nop 1
	v_permlane32_swap_b32_e32 v230, v231
	ds_read_b64_tr_b16 v[224:225], v174 offset:0x6400
	ds_read_b64_tr_b16 v[226:227], v174 offset:0x6c00
	v_mfma_f32_32x32x16_bf16 v[32:47], v[202:205], v[238:241], v[32:47]
	v_max_f32_e32 v231, v231, v231
	v_max_f32_e32 v230, v230, v230
	v_max_f32_e32 v230, v230, v231
	ds_read_b64_tr_b16 v[238:239], v174 offset:0x7400
	ds_read_b64_tr_b16 v[240:241], v174 offset:0x7c00
	s_waitcnt lgkmcnt(0)
	v_mfma_f32_32x32x16_bf16 v[16:31], v[146:149], v[208:211], v[16:31]
	v_sub_f32_e32 v231, v230, v187
	v_mul_f32_e32 v231, 0x3db504f3, v231
	s_mov_b32 s6, 0x41000000
	ds_read_b64_tr_b16 v[208:209], v174 offset:0x4600
	ds_read_b64_tr_b16 v[210:211], v174 offset:0x4e00
	v_mfma_f32_32x32x16_bf16 v[16:31], v[194:197], v[220:223], v[16:31]
	v_cmp_ge_f32_e32 vcc, s6, v231
	v_max_f32_e32 v231, v187, v187
	v_max_f32_e32 v231, v231, v230
	ds_read_b64_tr_b16 v[220:221], v174 offset:0x5600
	ds_read_b64_tr_b16 v[222:223], v174 offset:0x5e00
	v_mfma_f32_32x32x16_bf16 v[16:31], v[198:201], v[224:227], v[16:31]
	v_sub_f32_e32 v230, v187, v231
	v_mul_f32_e32 v230, 0x3e0293ee, v230
	v_exp_f32_e32 v230, v230
	ds_read_b64_tr_b16 v[224:225], v174 offset:0x6600
	ds_read_b64_tr_b16 v[226:227], v174 offset:0x6e00
	v_mfma_f32_32x32x16_bf16 v[16:31], v[202:205], v[238:241], v[16:31]
	ds_read_b64_tr_b16 v[238:239], v174 offset:0x7600
	ds_read_b64_tr_b16 v[240:241], v174 offset:0x7e00
	s_waitcnt lgkmcnt(0)
	v_mfma_f32_32x32x16_bf16 v[0:15], v[146:149], v[208:211], v[0:15]
	v_mfma_f32_32x32x16_bf16 v[0:15], v[194:197], v[220:223], v[0:15]
	v_mfma_f32_32x32x16_bf16 v[0:15], v[198:201], v[224:227], v[0:15]
	v_mfma_f32_32x32x16_bf16 v[0:15], v[202:205], v[238:241], v[0:15]
	s_nop 0
	v_mov_b32_e32 v146, v230
	v_mov_b32_e32 v147, v231
	s_branch .Lpvj_1167b

.Lpvj_1167b:
	s_cmp_eq_u64 vcc, exec
	s_cselect_b64 s[6:7], -1, 0
	s_barrier
	s_waitcnt vmcnt(0)
	v_cndmask_b32_e64 v146, v146, 1.0, s[6:7]
	v_cmp_gt_f32_e32 vcc, 1.0, v146
	s_waitcnt vmcnt(0)
	ds_write_b128 v184, v[242:245] offset:16384
	ds_write_b128 v185, v[246:249] offset:16384
	s_cbranch_vccz .LBB0_1179
	s_and_saveexec_b64 s[8:9], s[4:5]
	ds_write_b32 v173, v146 offset:128
	s_or_b64 exec, exec, s[8:9]
	s_waitcnt lgkmcnt(0)
	ds_read_b128 v[130:133], v169 offset:224
	ds_read_b128 v[134:137], v169 offset:192
	ds_read_b128 v[138:141], v169 offset:160
	ds_read_b128 v[142:145], v169 offset:128
	s_waitcnt lgkmcnt(3)
	v_pk_mul_f32 v[62:63], v[62:63], v[132:133]
	s_waitcnt lgkmcnt(2)
	v_pk_mul_f32 v[58:59], v[58:59], v[136:137]
	s_waitcnt lgkmcnt(1)
	v_pk_mul_f32 v[54:55], v[54:55], v[140:141]
	s_waitcnt lgkmcnt(0)
	v_pk_mul_f32 v[50:51], v[50:51], v[144:145]
	v_pk_mul_f32 v[60:61], v[60:61], v[130:131]
	v_pk_mul_f32 v[56:57], v[56:57], v[134:135]
	v_pk_mul_f32 v[52:53], v[52:53], v[138:139]
	v_pk_mul_f32 v[48:49], v[48:49], v[142:143]
	v_pk_mul_f32 v[46:47], v[46:47], v[132:133]
	v_pk_mul_f32 v[42:43], v[42:43], v[136:137]
	v_pk_mul_f32 v[38:39], v[38:39], v[140:141]
	v_pk_mul_f32 v[34:35], v[34:35], v[144:145]
	v_pk_mul_f32 v[44:45], v[44:45], v[130:131]
	v_pk_mul_f32 v[40:41], v[40:41], v[134:135]
	v_pk_mul_f32 v[36:37], v[36:37], v[138:139]
	v_pk_mul_f32 v[32:33], v[32:33], v[142:143]
	v_pk_mul_f32 v[30:31], v[30:31], v[132:133]
	v_pk_mul_f32 v[26:27], v[26:27], v[136:137]
	v_pk_mul_f32 v[22:23], v[22:23], v[140:141]
	v_pk_mul_f32 v[18:19], v[18:19], v[144:145]
	v_pk_mul_f32 v[28:29], v[28:29], v[130:131]
	v_pk_mul_f32 v[24:25], v[24:25], v[134:135]
	v_pk_mul_f32 v[20:21], v[20:21], v[138:139]
	v_pk_mul_f32 v[16:17], v[16:17], v[142:143]
	v_pk_mul_f32 v[14:15], v[14:15], v[132:133]
	v_pk_mul_f32 v[10:11], v[10:11], v[136:137]
	v_pk_mul_f32 v[6:7], v[6:7], v[140:141]
	v_pk_mul_f32 v[2:3], v[2:3], v[144:145]
	v_pk_mul_f32 v[12:13], v[12:13], v[130:131]
	v_pk_mul_f32 v[8:9], v[8:9], v[134:135]
	v_pk_mul_f32 v[4:5], v[4:5], v[138:139]
	v_pk_mul_f32 v[0:1], v[0:1], v[142:143]

.LBB0_1354:
	v_readfirstlane_b32 s8, v183
	v_lshrrev_b32_e32 v234, 4, v183
	v_lshl_add_u64 v[230:231], v[170:171], 0, v[96:97]
	s_mov_b32 s10, 0x14b40000
	s_mov_b32 s11, 0
	s_and_b32 s8, s8, 0xfffffc00
	v_and_b32_e32 v234, 0x70, v234
	v_lshl_add_u64 v[230:231], v[230:231], 0, s[10:11]
	s_add_i32 m0, s8, 0x8000
	v_xor_b32_e32 v230, v234, v230
	v_lshl_add_u64 v[242:243], v[168:169], 0, v[96:97]
	s_mov_b32 s10, 0x10000
	global_load_lds_dwordx4 v[230:231], off
	v_lshl_add_u64 v[230:231], v[230:231], 0, s[10:11]
	s_add_i32 m0, s8, 0xa000
	s_mov_b32 s10, 0x15c40000
	v_lshl_add_u64 v[242:243], v[242:243], 0, s[10:11]
	global_load_lds_dwordx4 v[230:231], off
	s_mov_b32 s10, 0x10000
	v_lshl_add_u64 v[246:247], v[242:243], 0, s[10:11]
	global_load_dwordx4 v[242:245], v[242:243], off
	global_load_dwordx4 v[246:249], v[246:247], off
	ds_read_b128 v[80:83], v193
	ds_read_b128 v[84:87], v193 offset:32
	ds_read_b128 v[64:67], v193 offset:128
	ds_read_b128 v[68:71], v193 offset:160
	ds_read_b128 v[88:91], v193 offset:64
	ds_read_b128 v[72:75], v193 offset:192
	ds_read_b128 v[92:95], v193 offset:96
	ds_read_b128 v[76:79], v193 offset:224
	ds_read_b128 v[130:133], v187 offset:49152
	s_waitcnt vmcnt(2)
	ds_read_b128 v[134:137], v187 offset:57344
	s_waitcnt vmcnt(1)
	v_exp_f32_e32 v138, v146
	v_add_f32_e32 v146, 0, v203
	v_add_f32_e32 v146, v204, v146
	s_waitcnt lgkmcnt(1)
	v_mfma_f32_32x32x16_bf16 v[80:95], v[130:133], v[126:129], v[80:95]
	v_add_f32_e32 v146, v205, v146
	v_add_f32_e32 v146, v207, v146
	v_add_f32_e32 v146, v208, v146
	v_add_f32_e32 v146, v210, v146
	v_add_f32_e32 v146, v206, v146
	v_add_f32_e32 v146, v209, v146
	v_add_f32_e32 v146, v173, v146
	s_waitcnt lgkmcnt(0)
	v_mfma_f32_32x32x16_bf16 v[64:79], v[134:137], v[126:129], v[64:79]
	ds_read_b128 v[130:133], v188 offset:49152
	ds_read_b128 v[134:137], v188 offset:57344
	v_add_f32_e32 v146, v175, v146
	v_add_f32_e32 v146, v198, v146
	v_add_f32_e32 v146, v201, v146
	v_add_f32_e32 v146, v174, v146
	v_add_f32_e32 v146, v199, v146
	v_add_f32_e32 v146, v200, v146
	s_waitcnt lgkmcnt(1)
	v_mfma_f32_32x32x16_bf16 v[80:95], v[130:133], v[122:125], v[80:95]
	v_add_f32_e32 v146, v202, v146
	v_exp_f32_e32 v139, v147
	v_exp_f32_e32 v140, v160
	v_exp_f32_e32 v141, v161
	s_waitcnt vmcnt(0)
	v_exp_f32_e32 v142, v154
	v_exp_f32_e32 v143, v155
	v_exp_f32_e32 v144, v148
	s_waitcnt lgkmcnt(0)
	v_mfma_f32_32x32x16_bf16 v[64:79], v[134:137], v[122:125], v[64:79]
	ds_read_b128 v[130:133], v186 offset:49152
	ds_read_b128 v[134:137], v186 offset:57344
	v_exp_f32_e32 v145, v149
	v_cvt_pk_bf16_f32 v147, v205, v207
	v_cvt_pk_bf16_f32 v148, v208, v210
	v_cvt_pk_bf16_f32 v149, v206, v209
	v_cvt_pk_bf16_f32 v160, v142, v143
	v_cvt_pk_bf16_f32 v161, v144, v145
	s_waitcnt lgkmcnt(1)
	v_mfma_f32_32x32x16_bf16 v[80:95], v[130:133], v[118:121], v[80:95]
	v_permlane32_swap_b32_e32 v147, v149
	s_waitcnt lgkmcnt(0)
	v_mfma_f32_32x32x16_bf16 v[64:79], v[134:137], v[118:121], v[64:79]
	ds_read_b128 v[130:133], v167 offset:49152
	ds_read_b128 v[134:137], v167 offset:57344
	s_waitcnt lgkmcnt(1)
	v_mfma_f32_32x32x16_bf16 v[80:95], v[130:133], v[114:117], v[80:95]
	s_waitcnt lgkmcnt(0)
	v_mfma_f32_32x32x16_bf16 v[64:79], v[134:137], v[114:117], v[64:79]
	ds_read_b128 v[130:133], v187 offset:49280
	ds_read_b128 v[134:137], v187 offset:57472
	s_waitcnt lgkmcnt(1)
	v_mfma_f32_32x32x16_bf16 v[80:95], v[130:133], v[110:113], v[80:95]
	s_waitcnt lgkmcnt(0)
	v_mfma_f32_32x32x16_bf16 v[64:79], v[134:137], v[110:113], v[64:79]
	ds_read_b128 v[130:133], v188 offset:49280
	ds_read_b128 v[134:137], v188 offset:57472
	s_waitcnt lgkmcnt(1)
	v_mfma_f32_32x32x16_bf16 v[80:95], v[130:133], v[106:109], v[80:95]
	s_waitcnt lgkmcnt(0)
	v_mfma_f32_32x32x16_bf16 v[64:79], v[134:137], v[106:109], v[64:79]
	ds_read_b128 v[130:133], v186 offset:49280
	ds_read_b128 v[134:137], v186 offset:57472
	s_waitcnt lgkmcnt(1)
	v_mfma_f32_32x32x16_bf16 v[80:95], v[130:133], v[102:105], v[80:95]
	s_waitcnt lgkmcnt(0)
	v_mfma_f32_32x32x16_bf16 v[64:79], v[134:137], v[102:105], v[64:79]
	ds_read_b128 v[130:133], v167 offset:49280
	ds_read_b128 v[134:137], v167 offset:57472
	s_waitcnt lgkmcnt(1)
	v_mfma_f32_32x32x16_bf16 v[80:95], v[130:133], v[98:101], v[80:95]
	v_exp_f32_e32 v130, v158
	v_exp_f32_e32 v131, v159
	v_exp_f32_e32 v132, v156
	v_exp_f32_e32 v133, v157
	v_add_f32_e32 v146, v130, v146
	v_add_f32_e32 v146, v131, v146
	v_add_f32_e32 v146, v132, v146
	s_waitcnt lgkmcnt(0)
	v_mfma_f32_32x32x16_bf16 v[64:79], v[134:137], v[98:101], v[64:79]
	v_exp_f32_e32 v134, v152
	v_exp_f32_e32 v135, v153
	v_exp_f32_e32 v136, v150
	v_exp_f32_e32 v137, v151
	v_add_f32_e32 v146, v133, v146
	v_add_f32_e32 v146, v134, v146
	v_add_f32_e32 v146, v135, v146
	v_add_f32_e32 v146, v136, v146
	v_add_f32_e32 v146, v137, v146
	v_add_f32_e32 v146, v138, v146
	v_add_f32_e32 v146, v139, v146
	v_add_f32_e32 v146, v140, v146
	v_add_f32_e32 v146, v141, v146
	v_add_f32_e32 v146, v142, v146
	v_add_f32_e32 v146, v143, v146
	v_add_f32_e32 v146, v144, v146
	v_add_f32_e32 v195, v145, v146
	v_mov_b32_e32 v196, v195
	s_nop 1
	v_permlane32_swap_b32_e32 v195, v196
	v_cvt_pk_bf16_f32 v146, v203, v204
	v_cvt_pk_bf16_f32 v150, v173, v175
	v_cvt_pk_bf16_f32 v151, v198, v201
	v_cvt_pk_bf16_f32 v152, v174, v199
	v_cvt_pk_bf16_f32 v153, v200, v202
	v_cvt_pk_bf16_f32 v154, v130, v131
	v_cvt_pk_bf16_f32 v155, v132, v133
	v_cvt_pk_bf16_f32 v156, v134, v135
	v_cvt_pk_bf16_f32 v157, v136, v137
	v_cvt_pk_bf16_f32 v158, v138, v139
	v_cvt_pk_bf16_f32 v159, v140, v141
	v_permlane32_swap_b32_e32 v146, v148
	v_permlane32_swap_b32_e32 v150, v152
	v_permlane32_swap_b32_e32 v151, v153
	v_permlane32_swap_b32_e32 v154, v156
	v_permlane32_swap_b32_e32 v155, v157
	v_permlane32_swap_b32_e32 v158, v160
	v_permlane32_swap_b32_e32 v159, v161
	v_lshl_add_u64 v[174:175], v[168:169], 0, v[96:97]
	v_lshl_add_u64 v[172:173], v[170:171], 0, v[96:97]
	s_sub_i32 s6, s92, 64
	s_cmp_le_i32 s6, s41
	s_cbranch_scc0 .Lpvm_1354a
	ds_read_b64_tr_b16 v[198:199], v180 offset:0
	ds_read_b64_tr_b16 v[200:201], v180 offset:0x800
	ds_read_b64_tr_b16 v[202:203], v180 offset:0x1000
	ds_read_b64_tr_b16 v[204:205], v180 offset:0x1800
	ds_read_b64_tr_b16 v[206:207], v180 offset:0x2000
	ds_read_b64_tr_b16 v[208:209], v180 offset:0x2800
	ds_read_b64_tr_b16 v[210:211], v180 offset:0x3000
	ds_read_b64_tr_b16 v[212:213], v180 offset:0x3800
	s_waitcnt lgkmcnt(0)
	s_nop 0
	v_mfma_f32_32x32x16_bf16 v[48:63], v[146:149], v[198:201], v[48:63]
	v_max_f32_e32 v230, v81, v81
	v_max_f32_e32 v231, v80, v80
	v_max_f32_e32 v230, v231, v230
	ds_read_b64_tr_b16 v[198:199], v180 offset:0x200
	ds_read_b64_tr_b16 v[200:201], v180 offset:0xa00
	v_mfma_f32_32x32x16_bf16 v[48:63], v[150:153], v[202:205], v[48:63]
	v_max3_f32 v230, v230, v82, v83
	v_max3_f32 v230, v230, v84, v85
	v_max3_f32 v230, v230, v86, v87
	ds_read_b64_tr_b16 v[202:203], v180 offset:0x1200
	ds_read_b64_tr_b16 v[204:205], v180 offset:0x1a00
	v_mfma_f32_32x32x16_bf16 v[48:63], v[154:157], v[206:209], v[48:63]
	v_max3_f32 v230, v230, v88, v89
	v_max3_f32 v230, v230, v90, v91
	v_max3_f32 v230, v230, v92, v93
	ds_read_b64_tr_b16 v[206:207], v180 offset:0x2200
	ds_read_b64_tr_b16 v[208:209], v180 offset:0x2a00
	v_mfma_f32_32x32x16_bf16 v[48:63], v[158:161], v[210:213], v[48:63]
	v_max3_f32 v230, v230, v94, v95
	v_max3_f32 v230, v230, v64, v65
	v_max3_f32 v230, v230, v66, v67
	ds_read_b64_tr_b16 v[210:211], v180 offset:0x3200
	ds_read_b64_tr_b16 v[212:213], v180 offset:0x3a00
	s_waitcnt lgkmcnt(0)
	v_mfma_f32_32x32x16_bf16 v[32:47], v[146:149], v[198:201], v[32:47]
	v_max3_f32 v230, v230, v68, v69
	v_max3_f32 v230, v230, v70, v71
	v_max3_f32 v230, v230, v72, v73
	ds_read_b64_tr_b16 v[198:199], v180 offset:0x400
	ds_read_b64_tr_b16 v[200:201], v180 offset:0xc00
	v_mfma_f32_32x32x16_bf16 v[32:47], v[150:153], v[202:205], v[32:47]
	v_max3_f32 v230, v230, v74, v75
	v_max3_f32 v230, v230, v76, v77
	v_max3_f32 v230, v230, v78, v79
	ds_read_b64_tr_b16 v[202:203], v180 offset:0x1400
	ds_read_b64_tr_b16 v[204:205], v180 offset:0x1c00
	v_mfma_f32_32x32x16_bf16 v[32:47], v[154:157], v[206:209], v[32:47]
	v_mov_b32_e32 v231, v230
	s_nop 1
	v_permlane32_swap_b32_e32 v230, v231
	ds_read_b64_tr_b16 v[206:207], v180 offset:0x2400
	ds_read_b64_tr_b16 v[208:209], v180 offset:0x2c00
	v_mfma_f32_32x32x16_bf16 v[32:47], v[158:161], v[210:213], v[32:47]
	v_max_f32_e32 v231, v231, v231
	v_max_f32_e32 v230, v230, v230
	v_max_f32_e32 v230, v230, v231
	ds_read_b64_tr_b16 v[210:211], v180 offset:0x3400
	ds_read_b64_tr_b16 v[212:213], v180 offset:0x3c00
	s_waitcnt lgkmcnt(0)
	v_mfma_f32_32x32x16_bf16 v[16:31], v[146:149], v[198:201], v[16:31]
	v_sub_f32_e32 v231, v230, v194
	v_mul_f32_e32 v231, 0x3db504f3, v231
	s_mov_b32 s6, 0x41000000
	ds_read_b64_tr_b16 v[198:199], v180 offset:0x600
	ds_read_b64_tr_b16 v[200:201], v180 offset:0xe00
	v_mfma_f32_32x32x16_bf16 v[16:31], v[150:153], v[202:205], v[16:31]
	v_cmp_ge_f32_e32 vcc, s6, v231
	v_max_f32_e32 v231, v194, v194
	v_max_f32_e32 v230, v231, v230
	ds_read_b64_tr_b16 v[202:203], v180 offset:0x1600
	ds_read_b64_tr_b16 v[204:205], v180 offset:0x1e00
	v_mfma_f32_32x32x16_bf16 v[16:31], v[154:157], v[206:209], v[16:31]
	v_sub_f32_e32 v231, v194, v230
	v_mul_f32_e32 v231, 0x3e0293ee, v231
	v_exp_f32_e32 v231, v231
	ds_read_b64_tr_b16 v[206:207], v180 offset:0x2600
	ds_read_b64_tr_b16 v[208:209], v180 offset:0x2e00
	v_mfma_f32_32x32x16_bf16 v[16:31], v[158:161], v[210:213], v[16:31]
	ds_read_b64_tr_b16 v[210:211], v180 offset:0x3600
	ds_read_b64_tr_b16 v[212:213], v180 offset:0x3e00
	s_waitcnt lgkmcnt(0)
	v_mfma_f32_32x32x16_bf16 v[0:15], v[146:149], v[198:201], v[0:15]
	v_mfma_f32_32x32x16_bf16 v[0:15], v[150:153], v[202:205], v[0:15]
	v_mfma_f32_32x32x16_bf16 v[0:15], v[154:157], v[206:209], v[0:15]
	v_mfma_f32_32x32x16_bf16 v[0:15], v[158:161], v[210:213], v[0:15]
	s_nop 0
	v_mov_b32_e32 v146, v230
	v_mov_b32_e32 v147, v231
	s_branch .Lpvj_1354a

.Lpvj_1354a:
	s_cmp_eq_u64 vcc, exec
	s_cselect_b64 s[6:7], -1, 0
	s_barrier
	s_waitcnt vmcnt(0)
	v_cndmask_b32_e64 v197, v147, 1.0, s[6:7]
	v_cmp_gt_f32_e32 vcc, 1.0, v197
	s_waitcnt vmcnt(0)
	ds_write_b128 v189, v[242:245]
	ds_write_b128 v190, v[246:249]
	s_cbranch_vccz .LBB0_1360
	s_and_saveexec_b64 s[8:9], s[4:5]
	ds_write_b32 v182, v197 offset:128
	s_or_b64 exec, exec, s[8:9]
	s_waitcnt lgkmcnt(0)
	ds_read_b128 v[148:151], v165 offset:224
	ds_read_b128 v[152:155], v165 offset:192
	ds_read_b128 v[156:159], v165 offset:160
	ds_read_b128 v[198:201], v165 offset:128
	s_waitcnt lgkmcnt(3)
	v_pk_mul_f32 v[62:63], v[62:63], v[150:151]
	s_waitcnt lgkmcnt(2)
	v_pk_mul_f32 v[58:59], v[58:59], v[154:155]
	s_waitcnt lgkmcnt(1)
	v_pk_mul_f32 v[54:55], v[54:55], v[158:159]
	s_waitcnt lgkmcnt(0)
	v_pk_mul_f32 v[50:51], v[50:51], v[200:201]
	v_pk_mul_f32 v[60:61], v[60:61], v[148:149]
	v_pk_mul_f32 v[56:57], v[56:57], v[152:153]
	v_pk_mul_f32 v[52:53], v[52:53], v[156:157]
	v_pk_mul_f32 v[48:49], v[48:49], v[198:199]
	v_pk_mul_f32 v[46:47], v[46:47], v[150:151]
	v_pk_mul_f32 v[42:43], v[42:43], v[154:155]
	v_pk_mul_f32 v[38:39], v[38:39], v[158:159]
	v_pk_mul_f32 v[34:35], v[34:35], v[200:201]
	v_pk_mul_f32 v[44:45], v[44:45], v[148:149]
	v_pk_mul_f32 v[40:41], v[40:41], v[152:153]
	v_pk_mul_f32 v[36:37], v[36:37], v[156:157]
	v_pk_mul_f32 v[32:33], v[32:33], v[198:199]
	v_pk_mul_f32 v[30:31], v[30:31], v[150:151]
	v_pk_mul_f32 v[26:27], v[26:27], v[154:155]
	v_pk_mul_f32 v[22:23], v[22:23], v[158:159]
	v_pk_mul_f32 v[18:19], v[18:19], v[200:201]
	v_pk_mul_f32 v[28:29], v[28:29], v[148:149]
	v_pk_mul_f32 v[24:25], v[24:25], v[152:153]
	v_pk_mul_f32 v[20:21], v[20:21], v[156:157]
	v_pk_mul_f32 v[16:17], v[16:17], v[198:199]
	v_pk_mul_f32 v[14:15], v[14:15], v[150:151]
	v_pk_mul_f32 v[10:11], v[10:11], v[154:155]
	v_pk_mul_f32 v[6:7], v[6:7], v[158:159]
	v_pk_mul_f32 v[2:3], v[2:3], v[200:201]
	v_pk_mul_f32 v[12:13], v[12:13], v[148:149]
	v_pk_mul_f32 v[8:9], v[8:9], v[152:153]
	v_pk_mul_f32 v[4:5], v[4:5], v[156:157]
	v_pk_mul_f32 v[0:1], v[0:1], v[198:199]

.LBB0_1518:
	v_readfirstlane_b32 s8, v186
	v_lshrrev_b32_e32 v234, 4, v186
	v_lshl_add_u64 v[230:231], v[172:173], 0, v[96:97]
	s_and_b32 s8, s8, 0xfffffc00
	v_and_b32_e32 v234, 0x70, v234
	s_add_i32 m0, s8, 0x8000
	v_xor_b32_e32 v230, v234, v230
	v_lshl_add_u64 v[242:243], v[170:171], 0, v[96:97]
	global_load_lds_dwordx4 v[230:231], off
	v_lshl_add_u64 v[230:231], v[168:169], 0, v[96:97]
	s_add_i32 m0, s8, 0xa000
	v_xor_b32_e32 v230, v234, v230
	v_lshl_add_u64 v[246:247], v[166:167], 0, v[96:97]
	global_load_lds_dwordx4 v[230:231], off
	global_load_dwordx4 v[242:245], v[242:243], off
	global_load_dwordx4 v[246:249], v[246:247], off
	ds_read_b128 v[80:83], v200
	ds_read_b128 v[84:87], v200 offset:32
	ds_read_b128 v[64:67], v200 offset:128
	ds_read_b128 v[68:71], v200 offset:160
	ds_read_b128 v[88:91], v200 offset:64
	ds_read_b128 v[72:75], v200 offset:192
	ds_read_b128 v[92:95], v200 offset:96
	ds_read_b128 v[76:79], v200 offset:224
	ds_read_b128 v[208:211], v194 offset:49152
	ds_read_b128 v[220:223], v194 offset:57344
	v_add_f32_e32 v146, 0, v147
	v_add_f32_e32 v146, v148, v146
	v_add_f32_e32 v146, v149, v146
	s_waitcnt lgkmcnt(1)
	v_mfma_f32_32x32x16_bf16 v[80:95], v[208:211], v[126:129], v[80:95]
	v_add_f32_e32 v146, v160, v146
	v_add_f32_e32 v146, v161, v146
	v_add_f32_e32 v146, v207, v146
	v_add_f32_e32 v146, v159, v146
	v_add_f32_e32 v146, v206, v146
	v_add_f32_e32 v146, v151, v146
	v_add_f32_e32 v146, v153, v146
	s_waitcnt lgkmcnt(0)
	v_mfma_f32_32x32x16_bf16 v[64:79], v[220:223], v[126:129], v[64:79]
	ds_read_b128 v[208:211], v195 offset:49152
	ds_read_b128 v[220:223], v195 offset:57344
	v_add_f32_e32 v146, v154, v146
	v_add_f32_e32 v146, v155, v146
	v_exp_f32_e32 v144, v144
	v_add_f32_e32 v146, v152, v146
	v_exp_f32_e32 v145, v145
	v_add_f32_e32 v146, v156, v146
	s_waitcnt lgkmcnt(1)
	v_mfma_f32_32x32x16_bf16 v[80:95], v[208:211], v[122:125], v[80:95]
	v_exp_f32_e32 v142, v142
	v_add_f32_e32 v146, v157, v146
	v_exp_f32_e32 v143, v143
	v_add_f32_e32 v146, v158, v146
	v_exp_f32_e32 v140, v140
	v_add_f32_e32 v146, v144, v146
	v_exp_f32_e32 v141, v141
	s_waitcnt lgkmcnt(0)
	v_mfma_f32_32x32x16_bf16 v[64:79], v[220:223], v[122:125], v[64:79]
	ds_read_b128 v[208:211], v193 offset:49152
	ds_read_b128 v[220:223], v193 offset:57344
	v_add_f32_e32 v146, v145, v146
	v_exp_f32_e32 v138, v138
	v_add_f32_e32 v146, v142, v146
	v_exp_f32_e32 v139, v139
	v_add_f32_e32 v146, v143, v146
	v_exp_f32_e32 v136, v136
	s_waitcnt lgkmcnt(1)
	v_mfma_f32_32x32x16_bf16 v[80:95], v[208:211], v[118:121], v[80:95]
	v_add_f32_e32 v146, v140, v146
	v_exp_f32_e32 v137, v137
	v_add_f32_e32 v146, v141, v146
	v_exp_f32_e32 v134, v134
	v_add_f32_e32 v146, v138, v146
	v_exp_f32_e32 v135, v135
	v_add_f32_e32 v146, v139, v146
	s_waitcnt lgkmcnt(0)
	v_mfma_f32_32x32x16_bf16 v[64:79], v[220:223], v[118:121], v[64:79]
	ds_read_b128 v[208:211], v192 offset:49152
	ds_read_b128 v[220:223], v192 offset:57344
	v_exp_f32_e32 v132, v132
	v_add_f32_e32 v146, v136, v146
	v_exp_f32_e32 v133, v133
	v_add_f32_e32 v146, v137, v146
	v_exp_f32_e32 v130, v130
	v_add_f32_e32 v146, v134, v146
	s_waitcnt lgkmcnt(1)
	v_mfma_f32_32x32x16_bf16 v[80:95], v[208:211], v[114:117], v[80:95]
	v_exp_f32_e32 v131, v131
	v_add_f32_e32 v146, v135, v146
	v_add_f32_e32 v146, v132, v146
	v_add_f32_e32 v146, v133, v146
	v_add_f32_e32 v146, v130, v146
	v_add_f32_e32 v203, v131, v146
	v_mov_b32_e32 v204, v203
	s_waitcnt lgkmcnt(0)
	v_mfma_f32_32x32x16_bf16 v[64:79], v[220:223], v[114:117], v[64:79]
	ds_read_b128 v[208:211], v194 offset:49280
	ds_read_b128 v[220:223], v194 offset:57472
	v_permlane32_swap_b32_e32 v203, v204
	v_cvt_pk_bf16_f32 v146, v147, v148
	v_cvt_pk_bf16_f32 v147, v149, v160
	v_cvt_pk_bf16_f32 v148, v161, v207
	v_cvt_pk_bf16_f32 v149, v159, v206
	s_waitcnt lgkmcnt(1)
	v_mfma_f32_32x32x16_bf16 v[80:95], v[208:211], v[110:113], v[80:95]
	v_cvt_pk_bf16_f32 v206, v151, v153
	v_cvt_pk_bf16_f32 v207, v154, v155
	v_cvt_pk_bf16_f32 v153, v142, v143
	v_cvt_pk_bf16_f32 v154, v140, v141
	v_cvt_pk_bf16_f32 v155, v138, v139
	v_cvt_pk_bf16_f32 v159, v130, v131
	v_permlane32_swap_b32_e32 v146, v148
	s_waitcnt lgkmcnt(0)
	v_mfma_f32_32x32x16_bf16 v[64:79], v[220:223], v[110:113], v[64:79]
	ds_read_b128 v[208:211], v195 offset:49280
	ds_read_b128 v[220:223], v195 offset:57472
	v_permlane32_swap_b32_e32 v147, v149
	v_permlane32_swap_b32_e32 v153, v155
	s_waitcnt lgkmcnt(1)
	v_mfma_f32_32x32x16_bf16 v[80:95], v[208:211], v[106:109], v[80:95]
	s_waitcnt lgkmcnt(0)
	v_mfma_f32_32x32x16_bf16 v[64:79], v[220:223], v[106:109], v[64:79]
	ds_read_b128 v[208:211], v193 offset:49280
	ds_read_b128 v[220:223], v193 offset:57472
	s_waitcnt lgkmcnt(1)
	v_mfma_f32_32x32x16_bf16 v[80:95], v[208:211], v[102:105], v[80:95]
	s_waitcnt lgkmcnt(0)
	v_mfma_f32_32x32x16_bf16 v[64:79], v[220:223], v[102:105], v[64:79]
	ds_read_b128 v[208:211], v192 offset:49280
	ds_read_b128 v[220:223], v192 offset:57472
	s_waitcnt lgkmcnt(1)
	v_mfma_f32_32x32x16_bf16 v[80:95], v[208:211], v[98:101], v[80:95]
	v_cvt_pk_bf16_f32 v208, v152, v156
	v_cvt_pk_bf16_f32 v209, v157, v158
	v_cvt_pk_bf16_f32 v152, v144, v145
	v_cvt_pk_bf16_f32 v156, v136, v137
	v_cvt_pk_bf16_f32 v157, v134, v135
	v_cvt_pk_bf16_f32 v158, v132, v133
	v_permlane32_swap_b32_e32 v206, v208
	s_waitcnt lgkmcnt(0)
	v_mfma_f32_32x32x16_bf16 v[64:79], v[220:223], v[98:101], v[64:79]
	v_permlane32_swap_b32_e32 v207, v209
	v_permlane32_swap_b32_e32 v152, v154
	v_permlane32_swap_b32_e32 v156, v158
	v_permlane32_swap_b32_e32 v157, v159
	s_sub_i32 s6, s74, 64
	s_cmp_le_i32 s6, s3
	s_cbranch_scc0 .Lpvm_1518a
	ds_read_b64_tr_b16 v[210:211], v188 offset:0
	ds_read_b64_tr_b16 v[212:213], v188 offset:0x800
	ds_read_b64_tr_b16 v[220:221], v188 offset:0x1000
	ds_read_b64_tr_b16 v[222:223], v188 offset:0x1800
	ds_read_b64_tr_b16 v[224:225], v188 offset:0x2000
	ds_read_b64_tr_b16 v[226:227], v188 offset:0x2800
	ds_read_b64_tr_b16 v[238:239], v188 offset:0x3000
	ds_read_b64_tr_b16 v[240:241], v188 offset:0x3800
	s_waitcnt lgkmcnt(0)
	s_nop 0
	v_mfma_f32_32x32x16_bf16 v[0:15], v[146:149], v[210:213], v[0:15]
	v_max_f32_e32 v230, v81, v81
	v_max_f32_e32 v231, v80, v80
	v_max_f32_e32 v230, v231, v230
	ds_read_b64_tr_b16 v[210:211], v188 offset:0x200
	ds_read_b64_tr_b16 v[212:213], v188 offset:0xa00
	v_mfma_f32_32x32x16_bf16 v[0:15], v[206:209], v[220:223], v[0:15]
	v_max3_f32 v230, v230, v82, v83
	v_max3_f32 v230, v230, v84, v85
	v_max3_f32 v230, v230, v86, v87
	ds_read_b64_tr_b16 v[220:221], v188 offset:0x1200
	ds_read_b64_tr_b16 v[222:223], v188 offset:0x1a00
	v_mfma_f32_32x32x16_bf16 v[0:15], v[152:155], v[224:227], v[0:15]
	v_max3_f32 v230, v230, v88, v89
	v_max3_f32 v230, v230, v90, v91
	v_max3_f32 v230, v230, v92, v93
	ds_read_b64_tr_b16 v[224:225], v188 offset:0x2200
	ds_read_b64_tr_b16 v[226:227], v188 offset:0x2a00
	v_mfma_f32_32x32x16_bf16 v[0:15], v[156:159], v[238:241], v[0:15]
	v_max3_f32 v230, v230, v94, v95
	v_max3_f32 v230, v230, v64, v65
	v_max3_f32 v230, v230, v66, v67
	ds_read_b64_tr_b16 v[238:239], v188 offset:0x3200
	ds_read_b64_tr_b16 v[240:241], v188 offset:0x3a00
	s_waitcnt lgkmcnt(0)
	v_mfma_f32_32x32x16_bf16 v[48:63], v[146:149], v[210:213], v[48:63]
	v_max3_f32 v230, v230, v68, v69
	v_max3_f32 v230, v230, v70, v71
	v_max3_f32 v230, v230, v72, v73
	ds_read_b64_tr_b16 v[210:211], v188 offset:0x400
	ds_read_b64_tr_b16 v[212:213], v188 offset:0xc00
	v_mfma_f32_32x32x16_bf16 v[48:63], v[206:209], v[220:223], v[48:63]
	v_max3_f32 v230, v230, v74, v75
	v_max3_f32 v230, v230, v76, v77
	v_max3_f32 v230, v230, v78, v79
	ds_read_b64_tr_b16 v[220:221], v188 offset:0x1400
	ds_read_b64_tr_b16 v[222:223], v188 offset:0x1c00
	v_mfma_f32_32x32x16_bf16 v[48:63], v[152:155], v[224:227], v[48:63]
	v_mov_b32_e32 v231, v230
	s_nop 1
	v_permlane32_swap_b32_e32 v230, v231
	ds_read_b64_tr_b16 v[224:225], v188 offset:0x2400
	ds_read_b64_tr_b16 v[226:227], v188 offset:0x2c00
	v_mfma_f32_32x32x16_bf16 v[48:63], v[156:159], v[238:241], v[48:63]
	v_max_f32_e32 v231, v231, v231
	v_max_f32_e32 v230, v230, v230
	v_max_f32_e32 v230, v230, v231
	ds_read_b64_tr_b16 v[238:239], v188 offset:0x3400
	ds_read_b64_tr_b16 v[240:241], v188 offset:0x3c00
	s_waitcnt lgkmcnt(0)
	v_mfma_f32_32x32x16_bf16 v[32:47], v[146:149], v[210:213], v[32:47]
	v_sub_f32_e32 v231, v230, v150
	v_mul_f32_e32 v231, 0x3db504f3, v231
	s_mov_b32 s6, 0x41000000
	ds_read_b64_tr_b16 v[210:211], v188 offset:0x600
	ds_read_b64_tr_b16 v[212:213], v188 offset:0xe00
	v_mfma_f32_32x32x16_bf16 v[32:47], v[206:209], v[220:223], v[32:47]
	v_cmp_ge_f32_e32 vcc, s6, v231
	v_max_f32_e32 v231, v150, v150
	v_max_f32_e32 v230, v231, v230
	ds_read_b64_tr_b16 v[220:221], v188 offset:0x1600
	ds_read_b64_tr_b16 v[222:223], v188 offset:0x1e00
	v_mfma_f32_32x32x16_bf16 v[32:47], v[152:155], v[224:227], v[32:47]
	v_sub_f32_e32 v231, v150, v230
	v_mul_f32_e32 v231, 0x3e0293ee, v231
	v_exp_f32_e32 v231, v231
	ds_read_b64_tr_b16 v[224:225], v188 offset:0x2600
	ds_read_b64_tr_b16 v[226:227], v188 offset:0x2e00
	v_mfma_f32_32x32x16_bf16 v[32:47], v[156:159], v[238:241], v[32:47]
	ds_read_b64_tr_b16 v[238:239], v188 offset:0x3600
	ds_read_b64_tr_b16 v[240:241], v188 offset:0x3e00
	s_waitcnt lgkmcnt(0)
	v_mfma_f32_32x32x16_bf16 v[16:31], v[146:149], v[210:213], v[16:31]
	v_mfma_f32_32x32x16_bf16 v[16:31], v[206:209], v[220:223], v[16:31]
	v_mfma_f32_32x32x16_bf16 v[16:31], v[152:155], v[224:227], v[16:31]
	v_mfma_f32_32x32x16_bf16 v[16:31], v[156:159], v[238:241], v[16:31]
	s_nop 0
	v_mov_b32_e32 v146, v230
	v_mov_b32_e32 v147, v231
	s_branch .Lpvj_1518a

.Lpvj_1518a:
	s_cmp_eq_u64 vcc, exec
	s_cselect_b64 s[6:7], -1, 0
	s_barrier
	s_waitcnt vmcnt(0)
	v_cndmask_b32_e64 v205, v147, 1.0, s[6:7]
	v_cmp_gt_f32_e32 vcc, 1.0, v205
	s_waitcnt vmcnt(0)
	ds_write_b128 v197, v[242:245]
	ds_write_b128 v198, v[246:249]
	s_cbranch_vccz .LBB0_1524
	s_and_saveexec_b64 s[8:9], s[4:5]
	ds_write_b32 v201, v205 offset:128
	s_or_b64 exec, exec, s[8:9]
	s_waitcnt lgkmcnt(0)
	ds_read_b128 v[152:155], v191 offset:224
	ds_read_b128 v[156:159], v191 offset:192
	ds_read_b128 v[206:209], v191 offset:160
	ds_read_b128 v[210:213], v191 offset:128
	s_waitcnt lgkmcnt(3)
	v_pk_mul_f32 v[14:15], v[14:15], v[154:155]
	s_waitcnt lgkmcnt(2)
	v_pk_mul_f32 v[10:11], v[10:11], v[158:159]
	s_waitcnt lgkmcnt(1)
	v_pk_mul_f32 v[6:7], v[6:7], v[208:209]
	s_waitcnt lgkmcnt(0)
	v_pk_mul_f32 v[2:3], v[2:3], v[212:213]
	v_pk_mul_f32 v[12:13], v[12:13], v[152:153]
	v_pk_mul_f32 v[8:9], v[8:9], v[156:157]
	v_pk_mul_f32 v[4:5], v[4:5], v[206:207]
	v_pk_mul_f32 v[0:1], v[0:1], v[210:211]
	v_pk_mul_f32 v[62:63], v[62:63], v[154:155]
	v_pk_mul_f32 v[58:59], v[58:59], v[158:159]
	v_pk_mul_f32 v[54:55], v[54:55], v[208:209]
	v_pk_mul_f32 v[50:51], v[50:51], v[212:213]
	v_pk_mul_f32 v[60:61], v[60:61], v[152:153]
	v_pk_mul_f32 v[56:57], v[56:57], v[156:157]
	v_pk_mul_f32 v[52:53], v[52:53], v[206:207]
	v_pk_mul_f32 v[48:49], v[48:49], v[210:211]
	v_pk_mul_f32 v[46:47], v[46:47], v[154:155]
	v_pk_mul_f32 v[42:43], v[42:43], v[158:159]
	v_pk_mul_f32 v[38:39], v[38:39], v[208:209]
	v_pk_mul_f32 v[34:35], v[34:35], v[212:213]
	v_pk_mul_f32 v[44:45], v[44:45], v[152:153]
	v_pk_mul_f32 v[40:41], v[40:41], v[156:157]
	v_pk_mul_f32 v[36:37], v[36:37], v[206:207]
	v_pk_mul_f32 v[32:33], v[32:33], v[210:211]
	v_pk_mul_f32 v[30:31], v[30:31], v[154:155]
	v_pk_mul_f32 v[26:27], v[26:27], v[158:159]
	v_pk_mul_f32 v[22:23], v[22:23], v[208:209]
	v_pk_mul_f32 v[18:19], v[18:19], v[212:213]
	v_pk_mul_f32 v[28:29], v[28:29], v[152:153]
	v_pk_mul_f32 v[24:25], v[24:25], v[156:157]
	v_pk_mul_f32 v[20:21], v[20:21], v[206:207]
	v_pk_mul_f32 v[16:17], v[16:17], v[210:211]
